# P2a spatial epilogue: the eight u/gate loads of a unit issued together (were four load-pair/drain rounds behind stores)
# speedup vs baseline: 1.0107x; 1.0107x over previous
.LBB0_291:
	s_or_b64 exec, exec, s[0:1]
	v_lshl_add_u64 v[42:43], s[38:39], 0, v[20:21]
	v_mov_b64_e32 v[56:57], s[36:37]
	s_lshl_b32 s0, s59, 6
	s_lshl_b32 s52, s59, 9
	v_mad_u64_u32 v[56:57], s[38:39], v42, s75, v[56:57]
	v_lshl_add_u64 v[40:41], v[32:33], 0, s[52:53]
	v_mad_i32_i24 v57, v43, s75, v57
	s_lshl_b32 s52, s0, 1
	v_lshlrev_b64 v[42:43], 11, v[42:43]
	v_lshl_add_u64 v[56:57], v[56:57], 0, s[52:53]
	v_lshl_add_u64 v[42:43], s[18:19], 0, v[42:43]
	v_mov_b32_e32 v39, v1
	v_lshl_add_u64 v[58:59], v[42:43], 0, s[52:53]
	v_lshl_add_u64 v[42:43], v[56:57], 0, v[38:39]
	s_movk_i32 s41, 0x1000
	v_add_co_u32_e32 v42, vcc, s41, v42
	global_load_dword v40, v[40:41], off
	s_nop 0
	v_addc_co_u32_e32 v43, vcc, 0, v43, vcc
	global_load_dwordx2 v[56:57], v[42:43], off offset:2048
	global_load_dwordx2 v[60:61], v[42:43], off offset:3072
	global_load_dwordx2 v[68:69], v[42:43], off offset:2064
	global_load_dwordx2 v[70:71], v[42:43], off offset:3088
	global_load_dwordx2 v[72:73], v[42:43], off offset:2080
	global_load_dwordx2 v[74:75], v[42:43], off offset:3104
	global_load_dwordx2 v[76:77], v[42:43], off offset:2096
	global_load_dwordx2 v[78:79], v[42:43], off offset:3120
	s_mov_b64 s[0:1], 0xb200600
	s_waitcnt vmcnt(0)
	v_lshlrev_b32_e32 v66, 16, v56
	s_waitcnt vmcnt(0)
	v_lshlrev_b32_e32 v62, 16, v60
	v_mul_f32_e32 v41, 0xbfb8aa3b, v62
	v_exp_f32_e32 v41, v41
	v_and_b32_e32 v63, 0xffff0000, v60
	v_lshlrev_b32_e32 v60, 16, v61
	v_and_b32_e32 v61, 0xffff0000, v61
	v_add_f32_e32 v41, 1.0, v41
	v_rcp_f32_e32 v64, v41
	v_pk_add_f32 v[2:3], v[40:41], v[2:3] op_sel_hi:[0,1]
	v_mul_f32_e32 v41, 0xbfb8aa3b, v63
	v_exp_f32_e32 v41, v41
	v_and_b32_e32 v67, 0xffff0000, v56
	v_pk_mul_f32 v[2:3], v[2:3], v[66:67]
	v_add_f32_e32 v41, 1.0, v41
	v_rcp_f32_e32 v65, v41
	v_mul_f32_e32 v41, 0xbfb8aa3b, v60
	v_exp_f32_e32 v41, v41
	v_pk_mul_f32 v[62:63], v[64:65], v[62:63]
	s_nop 0
	v_pk_mul_f32 v[2:3], v[2:3], v[62:63]
	v_add_f32_e32 v41, 1.0, v41
	v_rcp_f32_e32 v56, v41
	v_pk_add_f32 v[4:5], v[40:41], v[4:5] op_sel_hi:[0,1]
	v_mul_f32_e32 v41, 0xbfb8aa3b, v61
	v_exp_f32_e32 v41, v41
	v_lshlrev_b32_e32 v62, 16, v57
	v_and_b32_e32 v63, 0xffff0000, v57
	v_pk_mul_f32 v[4:5], v[4:5], v[62:63]
	v_add_f32_e32 v41, 1.0, v41
	v_rcp_f32_e32 v57, v41
	v_pk_add_f32 v[6:7], v[40:41], v[6:7] op_sel_hi:[0,1]
	v_pk_add_f32 v[8:9], v[40:41], v[8:9] op_sel_hi:[0,1]
	v_pk_add_f32 v[10:11], v[40:41], v[10:11] op_sel_hi:[0,1]
	v_pk_mul_f32 v[56:57], v[56:57], v[60:61]
	v_pk_add_f32 v[12:13], v[40:41], v[12:13] op_sel_hi:[0,1]
	v_pk_mul_f32 v[4:5], v[4:5], v[56:57]
	v_cvt_pk_bf16_f32 v56, v2, v3
	v_cvt_pk_bf16_f32 v57, v4, v5
	v_lshl_add_u64 v[4:5], v[58:59], 0, v[38:39]
	v_lshl_add_u64 v[2:3], v[4:5], 0, s[0:1]
	s_mov_b32 s0, 0xb200000
	v_add_co_u32_e32 v4, vcc, s0, v4
	v_pk_add_f32 v[14:15], v[40:41], v[14:15] op_sel_hi:[0,1]
	s_nop 0
	v_addc_co_u32_e32 v5, vcc, 0, v5, vcc
	global_store_dwordx2 v[4:5], v[56:57], off offset:1536
	s_nop 0
	v_mov_b64_e32 v[4:5], v[68:69]
	v_mov_b64_e32 v[56:57], v[70:71]
	v_readlane_b32 s0, v251, 26
	s_add_i32 s58, s58, s0
	s_cmpk_gt_i32 s58, 0x3ff
	v_readlane_b32 s1, v251, 27
	v_lshlrev_b32_e32 v62, 16, v4
	v_lshlrev_b32_e32 v58, 16, v56
	v_and_b32_e32 v59, 0xffff0000, v56
	v_mul_f32_e32 v39, 0xbfb8aa3b, v58
	v_and_b32_e32 v63, 0xffff0000, v4
	v_mul_f32_e32 v4, 0xbfb8aa3b, v59
	v_exp_f32_e32 v39, v39
	v_exp_f32_e32 v4, v4
	v_pk_mul_f32 v[6:7], v[6:7], v[62:63]
	v_lshlrev_b32_e32 v56, 16, v57
	v_add_f32_e32 v39, 1.0, v39
	v_add_f32_e32 v4, 1.0, v4
	v_rcp_f32_e32 v60, v39
	v_rcp_f32_e32 v61, v4
	v_and_b32_e32 v57, 0xffff0000, v57
	v_mul_f32_e32 v4, 0xbfb8aa3b, v56
	v_exp_f32_e32 v4, v4
	v_pk_mul_f32 v[58:59], v[60:61], v[58:59]
	v_add_f32_e32 v4, 1.0, v4
	v_pk_mul_f32 v[6:7], v[6:7], v[58:59]
	v_lshlrev_b32_e32 v58, 16, v5
	v_and_b32_e32 v59, 0xffff0000, v5
	v_mul_f32_e32 v5, 0xbfb8aa3b, v57
	v_exp_f32_e32 v5, v5
	v_rcp_f32_e32 v4, v4
	v_pk_mul_f32 v[8:9], v[8:9], v[58:59]
	v_cvt_pk_bf16_f32 v6, v6, v7
	v_add_f32_e32 v5, 1.0, v5
	v_rcp_f32_e32 v5, v5
	s_nop 0
	v_pk_mul_f32 v[4:5], v[4:5], v[56:57]
	s_nop 0
	v_pk_mul_f32 v[4:5], v[8:9], v[4:5]
	s_nop 0
	v_cvt_pk_bf16_f32 v7, v4, v5
	global_store_dwordx2 v[2:3], v[6:7], off offset:16
	s_nop 0
	v_mov_b64_e32 v[4:5], v[72:73]
	v_mov_b64_e32 v[6:7], v[74:75]
	v_lshlrev_b32_e32 v58, 16, v4
	v_lshlrev_b32_e32 v8, 16, v6
	v_and_b32_e32 v9, 0xffff0000, v6
	v_mul_f32_e32 v6, 0xbfb8aa3b, v8
	v_and_b32_e32 v59, 0xffff0000, v4
	v_mul_f32_e32 v4, 0xbfb8aa3b, v9
	v_exp_f32_e32 v6, v6
	v_exp_f32_e32 v4, v4
	v_pk_mul_f32 v[10:11], v[10:11], v[58:59]
	v_add_f32_e32 v6, 1.0, v6
	v_add_f32_e32 v4, 1.0, v4
	v_rcp_f32_e32 v56, v6
	v_rcp_f32_e32 v57, v4
	v_lshlrev_b32_e32 v6, 16, v7
	v_and_b32_e32 v7, 0xffff0000, v7
	v_mul_f32_e32 v4, 0xbfb8aa3b, v6
	v_pk_mul_f32 v[8:9], v[56:57], v[8:9]
	v_exp_f32_e32 v4, v4
	v_pk_mul_f32 v[8:9], v[10:11], v[8:9]
	v_lshlrev_b32_e32 v10, 16, v5
	v_and_b32_e32 v11, 0xffff0000, v5
	v_mul_f32_e32 v5, 0xbfb8aa3b, v7
	v_exp_f32_e32 v5, v5
	v_add_f32_e32 v4, 1.0, v4
	v_rcp_f32_e32 v4, v4
	v_pk_mul_f32 v[10:11], v[12:13], v[10:11]
	v_add_f32_e32 v5, 1.0, v5
	v_rcp_f32_e32 v5, v5
	s_nop 0
	v_pk_mul_f32 v[4:5], v[4:5], v[6:7]
	s_nop 0
	v_pk_mul_f32 v[4:5], v[10:11], v[4:5]
	v_cvt_pk_bf16_f32 v6, v8, v9
	v_cvt_pk_bf16_f32 v7, v4, v5
	global_store_dwordx2 v[2:3], v[6:7], off offset:32
	s_nop 0
	v_mov_b64_e32 v[4:5], v[76:77]
	v_mov_b64_e32 v[6:7], v[78:79]
	v_lshlrev_b32_e32 v12, 16, v4
	v_lshlrev_b32_e32 v8, 16, v6
	v_and_b32_e32 v9, 0xffff0000, v6
	v_mul_f32_e32 v6, 0xbfb8aa3b, v8
	v_and_b32_e32 v13, 0xffff0000, v4
	v_mul_f32_e32 v4, 0xbfb8aa3b, v9
	v_exp_f32_e32 v6, v6
	v_exp_f32_e32 v4, v4
	v_pk_mul_f32 v[12:13], v[14:15], v[12:13]
	v_add_f32_e32 v6, 1.0, v6
	v_add_f32_e32 v4, 1.0, v4
	v_rcp_f32_e32 v10, v6
	v_rcp_f32_e32 v11, v4
	v_lshlrev_b32_e32 v6, 16, v7
	v_and_b32_e32 v7, 0xffff0000, v7
	v_mul_f32_e32 v4, 0xbfb8aa3b, v6
	v_pk_mul_f32 v[8:9], v[10:11], v[8:9]
	v_lshlrev_b32_e32 v10, 16, v5
	v_and_b32_e32 v11, 0xffff0000, v5
	v_mul_f32_e32 v5, 0xbfb8aa3b, v7
	v_exp_f32_e32 v4, v4
	v_exp_f32_e32 v5, v5
	v_pk_mul_f32 v[8:9], v[12:13], v[8:9]
	v_pk_add_f32 v[12:13], v[40:41], v[16:17] op_sel_hi:[0,1]
	v_add_f32_e32 v4, 1.0, v4
	v_add_f32_e32 v5, 1.0, v5
	v_rcp_f32_e32 v4, v4
	v_rcp_f32_e32 v5, v5
	v_pk_mul_f32 v[10:11], v[12:13], v[10:11]
	v_pk_mul_f32 v[4:5], v[4:5], v[6:7]
	s_nop 0
	v_pk_mul_f32 v[4:5], v[10:11], v[4:5]
	v_cvt_pk_bf16_f32 v6, v8, v9
	v_cvt_pk_bf16_f32 v7, v4, v5
	global_store_dwordx2 v[2:3], v[6:7], off offset:48
	s_barrier
	s_cbranch_scc1 .LBB0_298
